# v24 + coalesced warm-up loads of the DFT item rows before the token-per-lane staging loads
# baseline (speedup 1.0000x reference)
; __device__ __forceinline__ void phase_prep(const Params& P, int l, unsigned char* lds) {
;     ...
;             for (int rep = 0; rep < 4; ++rep) {
;                 const int id = tid + 512 * rep, tok = id >> 5, ch = id & 31;
;                 const u32x4 w = *(const u32x4*)(proj + (size_t)(r0 + tok) * INW + PD_U + 8 * ch);
;                 f32x4 a0 = (f32x4){bflo(w.x), bfhi(w.x), bflo(w.y), bfhi(w.y)}, a1 = (f32x4){bflo(w.z), bfhi(w.z), bflo(w.w), bfhi(w.w)};
;                 float* d = U + tok * 256 + 8 * ch;
;                 if (!is_ctx) {
;                     const int tg = t0 - CTX + tok, mt = (tg == 0) ? SEQ / 2 : SEQ - tg;
;                     const u32x4 m = *(const u32x4*)(proj + ((size_t)b * TT + CTX + mt) * INW + PD_U + 8 * ch);
;                     const f32x4 m0 = (f32x4){bflo(m.x), bfhi(m.x), bflo(m.y), bfhi(m.y)}, m1 = (f32x4){bflo(m.z), bfhi(m.z), bflo(m.w), bfhi(m.w)};
;                     float* d2 = U2 + tok * 256 + 8 * ch;
;                     if (tg == 0) { *(f32x4*)d2 = m0; *(f32x4*)(d2 + 4) = m1; }
;                     else { *(f32x4*)d2 = a0 - m0; *(f32x4*)(d2 + 4) = a1 - m1; a0 = a0 + m0; a1 = a1 + m1; }
;                 }
.LBB0_232:
	s_cmpk_gt_i32 s64, 0xff
	s_cselect_b64 s[42:43], -1, 0
	s_cmpk_lt_i32 s64, 0x100
	s_cselect_b64 s[48:49], -1, 0
	s_andn2_b64 vcc, exec, s[38:39]
	s_mov_b64 s[38:39], -1
	s_cbranch_vccnz .LBB0_277
	v_and_b32_e32 v32, 63, v44
	v_lshrrev_b32_e32 v33, 5, v32
	v_and_b32_e32 v34, 31, v32
	v_readfirstlane_b32 s12, v44
	s_nop 3
	s_lshr_b32 s12, s12, 6
	s_and_b32 s13, s12, 1
	s_lshr_b32 s15, s12, 1
	v_lshrrev_b32_e32 v41, 5, v44
	v_and_b32_e32 v42, 31, v44
	v_lshlrev_b32_e32 v42, 4, v42
	v_add_u32_e32 v43, s29, v41
	v_mov_b64_e32 v[100:101], s[10:11]
	v_mad_u64_u32 v[102:103], s[18:19], v43, s23, v[100:101]
	v_add_u32_e32 v42, 0x1400, v42
	v_add_co_u32_e32 v102, vcc, v102, v42
	s_nop 1
	v_addc_co_u32_e32 v103, vcc, 0, v103, vcc
	global_load_dwordx4 v[46:49], v[102:103], off
	v_add_co_u32_e32 v102, vcc, 0x16000, v102
	s_nop 1
	v_addc_co_u32_e32 v103, vcc, 0, v103, vcc
	global_load_dwordx4 v[50:53], v[102:103], off
	v_add_co_u32_e32 v102, vcc, 0x16000, v102
	s_nop 1
	v_addc_co_u32_e32 v103, vcc, 0, v103, vcc
	global_load_dwordx4 v[54:57], v[102:103], off
	v_add_co_u32_e32 v102, vcc, 0x16000, v102
	s_nop 1
	v_addc_co_u32_e32 v103, vcc, 0, v103, vcc
	global_load_dwordx4 v[58:61], v[102:103], off
	s_and_b64 vcc, exec, s[42:43]
	s_cbranch_vccz .Ldft_warm_done
	v_add_u32_e32 v43, s64, v41
	v_add_u32_e32 v43, 0xffffff00, v43
	v_sub_u32_e32 v104, 0x800, v43
	v_cmp_ne_u32_e32 vcc, 0, v43
	s_nop 1
	v_cndmask_b32_e32 v104, v242, v104, vcc
	s_mul_i32 s18, s36, 0x900
	s_add_u32 s18, s18, 0x100
	v_add_u32_e32 v104, s18, v104
	v_mad_u64_u32 v[106:107], s[18:19], v104, s23, v[100:101]
	v_add_co_u32_e32 v106, vcc, v106, v42
	s_nop 1
	v_addc_co_u32_e32 v107, vcc, 0, v107, vcc
	global_load_dwordx4 v[62:65], v[106:107], off
	v_add_u32_e32 v43, s64, v41
	v_add_u32_e32 v43, 0xffffff10, v43
	v_sub_u32_e32 v104, 0x800, v43
	v_cmp_ne_u32_e32 vcc, 0, v43
	s_nop 1
	v_cndmask_b32_e32 v104, v242, v104, vcc
	s_mul_i32 s18, s36, 0x900
	s_add_u32 s18, s18, 0x100
	v_add_u32_e32 v104, s18, v104
	v_mad_u64_u32 v[106:107], s[18:19], v104, s23, v[100:101]
	v_add_co_u32_e32 v106, vcc, v106, v42
	s_nop 1
	v_addc_co_u32_e32 v107, vcc, 0, v107, vcc
	global_load_dwordx4 v[66:69], v[106:107], off
	v_add_u32_e32 v43, s64, v41
	v_add_u32_e32 v43, 0xffffff20, v43
	v_sub_u32_e32 v104, 0x800, v43
	v_cmp_ne_u32_e32 vcc, 0, v43
	s_nop 1
	v_cndmask_b32_e32 v104, v242, v104, vcc
	s_mul_i32 s18, s36, 0x900
	s_add_u32 s18, s18, 0x100
	v_add_u32_e32 v104, s18, v104
	v_mad_u64_u32 v[106:107], s[18:19], v104, s23, v[100:101]
	v_add_co_u32_e32 v106, vcc, v106, v42
	s_nop 1
	v_addc_co_u32_e32 v107, vcc, 0, v107, vcc
	global_load_dwordx4 v[70:73], v[106:107], off
	v_add_u32_e32 v43, s64, v41
	v_add_u32_e32 v43, 0xffffff30, v43
	v_sub_u32_e32 v104, 0x800, v43
	v_cmp_ne_u32_e32 vcc, 0, v43
	s_nop 1
	v_cndmask_b32_e32 v104, v242, v104, vcc
	s_mul_i32 s18, s36, 0x900
	s_add_u32 s18, s18, 0x100
	v_add_u32_e32 v104, s18, v104
	v_mad_u64_u32 v[106:107], s[18:19], v104, s23, v[100:101]
	v_add_co_u32_e32 v106, vcc, v106, v42
	s_nop 1
	v_addc_co_u32_e32 v107, vcc, 0, v107, vcc
	global_load_dwordx4 v[74:77], v[106:107], off
.Ldft_warm_done:
	s_waitcnt vmcnt(0)
	v_add_u32_e32 v41, s29, v32
	v_mov_b64_e32 v[100:101], s[10:11]
	v_mad_u64_u32 v[102:103], s[18:19], v41, s23, v[100:101]
	s_lshl_b32 s7, s12, 6
	s_add_u32 s7, s7, 0x1400
	v_add_co_u32_e32 v102, vcc, s7, v102
	s_nop 1
	v_addc_co_u32_e32 v103, vcc, 0, v103, vcc
	global_load_dwordx4 v[0:3], v[102:103], off
	global_load_dwordx4 v[4:7], v[102:103], off offset:16
	global_load_dwordx4 v[8:11], v[102:103], off offset:32
	global_load_dwordx4 v[12:15], v[102:103], off offset:48
	s_and_b64 vcc, exec, s[42:43]
	s_cbranch_vccz .Ldft_st_ctx
	v_add_u32_e32 v42, s64, v32
	v_add_u32_e32 v42, 0xffffff00, v42
	v_sub_u32_e32 v43, 0x800, v42
	v_cmp_ne_u32_e32 vcc, 0, v42
	s_nop 1
	v_cndmask_b32_e32 v43, v242, v43, vcc
	s_mul_i32 s18, s36, 0x900
	s_add_u32 s18, s18, 0x100
	v_add_u32_e32 v43, s18, v43
	v_mad_u64_u32 v[104:105], s[18:19], v43, s23, v[100:101]
	v_add_co_u32_e32 v104, vcc, s7, v104
	s_nop 1
	v_addc_co_u32_e32 v105, vcc, 0, v105, vcc
	global_load_dwordx4 v[16:19], v[104:105], off
	global_load_dwordx4 v[20:23], v[104:105], off offset:16
	global_load_dwordx4 v[24:27], v[104:105], off offset:32
	global_load_dwordx4 v[28:31], v[104:105], off offset:48

; __device__ __forceinline__ void phase_prep(const Params& P, int l, unsigned char* lds) {
;     ...
;             __syncthreads();
.Ldft_out_done:
	s_barrier
	s_mov_b64 s[38:39], 0
